# XCD locality: GEMM row ownership incl QKV, attention, LRU scans and S5 scans placed on the XCD that owns their token rows; up rounds reversed
# baseline (speedup 1.0000x reference)
; __device__ __forceinline__ int launder(int v) { asm volatile("" : "+v"(v)); return v; }
; __device__ __forceinline__ void lru_scan1(const bf16_t* Ab, const bf16_t* Bb, const bf16_t* XC, const float* lam, float* PE, int bid, int G) {
;     const int gtid = bid * NTHR + launder(threadIdx.x), nthreads = G * NTHR;
;     for (int item = gtid; item < LRU_NC * D; item += nthreads) {
;         const int ch = item & (D - 1), c = item >> 11;
.LBB0_740:
	s_or_b64 exec, exec, s[4:5]
	s_waitcnt lgkmcnt(0)
	s_barrier
	s_load_dwordx2 s[4:5], s[8:9], 0x40
	v_mov_b32_e32 v1, v246
	v_readlane_b32 s0, v254, 4
	s_cmp_lg_u32 s78, 0x100
	s_cbranch_scc1 .Llruperm_a
	s_lshr_b32 s100, s0, 9
	s_and_b32 s101, s100, 7
	s_lshl_b32 s101, s101, 5
	s_lshr_b32 s100, s100, 3
	s_or_b32 s100, s100, s101
	s_lshl_b32 s0, s100, 9
.Llruperm_a:
	s_nop 1
	v_add_u32_e32 v1, s0, v1
	s_mov_b32 s0, 0x20000
	v_cmp_gt_i32_e32 vcc, s0, v1
	s_and_saveexec_b64 s[6:7], vcc
	s_cbranch_execz .LBB0_810
	s_mov_b64 s[8:9], 0
	s_branch .LBB0_743

; __device__ __forceinline__ int launder(int v) { asm volatile("" : "+v"(v)); return v; }
; __device__ __forceinline__ void lru_scan2(const bf16_t* Ab, const bf16_t* Bb, const bf16_t* XC, const float* lam, const float* PE, const bf16_t* gate, bf16_t* Y, int bid, int G) {
;     const int gtid = bid * NTHR + launder(threadIdx.x), nthreads = G * NTHR;
;     for (int item = gtid; item < LRU_NC * D; item += nthreads) {
;         const int ch = item & (D - 1), c = item >> 11;
.LBB0_862:
	s_or_b64 exec, exec, s[6:7]
	s_waitcnt lgkmcnt(0)
	v_mov_b32_e32 v2, v246
	v_readlane_b32 s0, v254, 4
	s_cmp_lg_u32 s78, 0x100
	s_cbranch_scc1 .Llruperm_b
	s_lshr_b32 s100, s0, 9
	s_and_b32 s101, s100, 7
	s_lshl_b32 s101, s101, 5
	s_lshr_b32 s100, s100, 3
	s_or_b32 s100, s100, s101
	s_lshl_b32 s0, s100, 9
.Llruperm_b:
	s_barrier
	s_nop 0
	v_add_u32_e32 v1, s0, v2
	s_mov_b32 s0, 0x20000
	v_cmp_gt_i32_e32 vcc, s0, v1
	s_and_saveexec_b64 s[6:7], vcc
	s_cbranch_execz .LBB0_939
	v_readlane_b32 s0, v254, 4
	s_cmp_lg_u32 s78, 0x100
	s_cbranch_scc1 .Llruperm_c
	s_lshr_b32 s100, s0, 9
	s_and_b32 s101, s100, 7
	s_lshl_b32 s101, s101, 5
	s_lshr_b32 s100, s100, 3
	s_or_b32 s100, s100, s101
	s_lshl_b32 s0, s100, 9
.Llruperm_c:
	s_mov_b64 s[8:9], 0
	s_nop 0
	v_add_u16_e32 v22, s0, v2
	s_branch .LBB0_865

; #define LAS __attribute__((address_space(3)))
; __device__ __forceinline__ void s5_item_setup(const S5Params& P, int g, int lane, LAS unsigned char* wlds, S5Item& L) {
;     LAS float* zt = (LAS float*)(wlds + S5_OFF_Z);
;     {
;         const float lr = P.a_re[g * 64 + lane], li = P.a_im[g * 64 + lane], dt = expf(P.log_dt[g]);
;         const float mag = expf(lr * dt);
;         L.abr = mag * cosf(li * dt); L.abi = mag * sinf(li * dt);
; __device__ __forceinline__ void s5_scan1(LAS unsigned char* lds, const S5Params& P, const bf16_t* U, float* ES, int bid, int G) {
;     ...
;     for (int item = gw; item < 128 * S5_NC; item += ngw) {
;         const int g = item & 127, c = item >> 7;
;         S5Item L; s5_item_setup(P, g, lane, wlds, L);
.LBB0_1170:
	s_mov_b32 s101, s44
	s_cmp_lg_u32 s82, 0x800
	s_cbranch_scc1 .Ls5perm_a
	s_bfe_u32 s101, s44, 0x30003
	s_lshl_b32 s101, s101, 9
	s_bfe_u32 s100, s44, 0x2000a
	s_lshl_b32 s100, s100, 7
	s_or_b32 s101, s101, s100
	s_bfe_u32 s100, s44, 0x40006
	s_lshl_b32 s100, s100, 3
	s_or_b32 s101, s101, s100
	s_and_b32 s100, s44, 7
	s_or_b32 s101, s101, s100
.Ls5perm_a:
	s_and_b32 s0, s101, 0x7f
	s_lshl_b32 s1, s0, 2
	v_mov_b32_e32 v2, s1
	global_load_dword v4, v2, s[20:21]
	s_lshl_b32 s68, s0, 6
	v_or_b32_e32 v2, s68, v1
	v_lshlrev_b32_e32 v2, 2, v2
	global_load_dword v3, v2, s[18:19]
	s_nop 0
	global_load_dword v2, v2, s[16:17]
	s_mov_b32 s1, 0x3fb8aa3b
	s_waitcnt vmcnt(2)
	v_mul_f32_e32 v5, 0x3fb8aa3b, v4
	v_fma_f32 v6, v4, s1, -v5
	v_rndne_f32_e32 v7, v5
	v_fmac_f32_e32 v6, 0x32a5705f, v4
	v_sub_f32_e32 v5, v5, v7
	v_add_f32_e32 v5, v5, v6
	v_cvt_i32_f32_e32 v7, v7
	v_exp_f32_e32 v5, v5
	s_mov_b32 s1, 0xc2ce8ed0
	v_cmp_ngt_f32_e32 vcc, s1, v4
	s_mov_b32 s1, 0x42b17218
	v_ldexp_f32 v5, v5, v7
	v_cndmask_b32_e32 v5, 0, v5, vcc
	v_cmp_nlt_f32_e32 vcc, s1, v4
	s_brev_b32 s1, 18
	s_nop 0
	v_cndmask_b32_e32 v6, v241, v5, vcc
	s_waitcnt vmcnt(1)
	v_mul_f32_e32 v4, v3, v6
	v_and_b32_e32 v5, 0x7fffffff, v4
	v_lshrrev_b32_e32 v7, 23, v5
	v_and_b32_e32 v8, 0x7fffff, v5
	v_cmp_nlt_f32_e64 s[14:15], |v4|, s1
	v_add_u32_e32 v10, 0xffffff88, v7
	v_or_b32_e32 v9, 0x800000, v8
	s_and_saveexec_b64 s[8:9], s[14:15]
	s_xor_b64 s[34:35], exec, s[8:9]
	s_cbranch_execz .LBB0_1172
	s_mov_b32 s1, 0xfe5163ab
	v_mad_u64_u32 v[12:13], s[12:13], v9, s1, 0
	v_mov_b32_e32 v14, v13
	v_mov_b32_e32 v15, v0
	s_mov_b32 s1, 0x3c439041
	v_mad_u64_u32 v[14:15], s[12:13], v9, s1, v[14:15]
	v_mov_b32_e32 v16, v15
	v_mov_b32_e32 v17, v0
	s_mov_b32 s1, 0xdb629599
	v_mad_u64_u32 v[16:17], s[12:13], v9, s1, v[16:17]
	v_cmp_lt_u32_e32 vcc, 63, v10
	v_not_b32_e32 v7, 63
	v_mov_b32_e32 v18, v17
	v_mov_b32_e32 v19, v0
	s_mov_b32 s1, 0xf534ddc0
	v_cndmask_b32_e32 v7, 0, v7, vcc
	v_mad_u64_u32 v[18:19], s[12:13], v9, s1, v[18:19]
	v_add_u32_e32 v7, v7, v10
	v_mov_b32_e32 v20, v19
	v_mov_b32_e32 v21, v0
	s_mov_b32 s1, 0xfc2757d1
	v_cmp_lt_u32_e64 s[8:9], 31, v7
	v_not_b32_e32 v11, 31
	v_mad_u64_u32 v[20:21], s[12:13], v9, s1, v[20:21]
	v_cndmask_b32_e64 v8, 0, v11, s[8:9]
	v_mov_b32_e32 v22, v21
	v_mov_b32_e32 v23, v0
	s_mov_b32 s1, 0x4e441529
	v_add_u32_e32 v7, v8, v7
	v_mad_u64_u32 v[22:23], s[12:13], v9, s1, v[22:23]
	v_cmp_lt_u32_e64 s[10:11], 31, v7
	v_mov_b32_e32 v24, v23
	v_mov_b32_e32 v25, v0
	s_mov_b32 s1, 0xa2f9836e
	v_cndmask_b32_e64 v8, 0, v11, s[10:11]
	v_mad_u64_u32 v[24:25], s[12:13], v9, s1, v[24:25]
	v_add_u32_e32 v7, v8, v7
	v_cndmask_b32_e32 v8, v22, v18, vcc
	v_cndmask_b32_e32 v11, v24, v20, vcc
	v_cndmask_b32_e32 v15, v25, v22, vcc
	v_cndmask_b32_e64 v13, v11, v8, s[8:9]
	v_cndmask_b32_e64 v11, v15, v11, s[8:9]
	v_cndmask_b32_e32 v15, v20, v16, vcc
	v_cndmask_b32_e64 v8, v8, v15, s[8:9]
	v_cndmask_b32_e64 v11, v11, v13, s[10:11]
	v_cndmask_b32_e64 v13, v13, v8, s[10:11]
	v_sub_u32_e32 v17, 32, v7
	v_alignbit_b32 v19, v11, v13, v17
	v_cmp_eq_u32_e64 s[12:13], 0, v7
	v_cndmask_b32_e32 v12, v16, v12, vcc
	s_mov_b32 s1, 0x3fc90fda
	v_cndmask_b32_e64 v7, v19, v11, s[12:13]
	v_cndmask_b32_e32 v11, v18, v14, vcc
	v_cndmask_b32_e64 v14, v15, v11, s[8:9]
	v_cndmask_b32_e64 v8, v8, v14, s[10:11]
	v_alignbit_b32 v15, v13, v8, v17
	v_cndmask_b32_e64 v11, v11, v12, s[8:9]
	v_cndmask_b32_e64 v13, v15, v13, s[12:13]
	v_bfe_u32 v19, v7, 29, 1
	v_cndmask_b32_e64 v11, v14, v11, s[10:11]
	v_alignbit_b32 v15, v7, v13, 30
	v_sub_u32_e32 v20, 0, v19
	v_alignbit_b32 v12, v8, v11, v17
	v_xor_b32_e32 v15, v15, v20
	v_cndmask_b32_e64 v8, v12, v8, s[12:13]
	v_alignbit_b32 v12, v13, v8, 30
	v_ffbh_u32_e32 v13, v15
	v_min_u32_e32 v13, 32, v13
	v_alignbit_b32 v8, v8, v11, 30
	v_xor_b32_e32 v12, v12, v20
	v_sub_u32_e32 v14, 31, v13
	v_xor_b32_e32 v8, v8, v20
	v_alignbit_b32 v15, v15, v12, v14
	v_alignbit_b32 v8, v12, v8, v14
	v_alignbit_b32 v11, v15, v8, 9
	v_ffbh_u32_e32 v12, v11
	v_min_u32_e32 v12, 32, v12
	v_lshrrev_b32_e32 v18, 29, v7
	v_not_b32_e32 v14, v12
	v_alignbit_b32 v8, v11, v8, v14
	v_lshlrev_b32_e32 v11, 31, v18
	v_or_b32_e32 v14, 0x33000000, v11
	v_add_lshl_u32 v12, v12, v13, 23
	v_lshrrev_b32_e32 v8, 9, v8
	v_sub_u32_e32 v12, v14, v12
	v_or_b32_e32 v11, 0.5, v11
	v_lshlrev_b32_e32 v13, 23, v13
	v_or_b32_e32 v8, v12, v8
	v_lshrrev_b32_e32 v12, 9, v15
	v_sub_u32_e32 v11, v11, v13
	v_or_b32_e32 v11, v12, v11
	v_mul_f32_e32 v12, 0x3fc90fda, v11
	v_fma_f32 v13, v11, s1, -v12
	v_fmac_f32_e32 v13, 0x33a22168, v11
	v_fmac_f32_e32 v13, 0x3fc90fda, v8
	v_lshrrev_b32_e32 v7, 30, v7
	v_add_f32_e32 v8, v12, v13
	v_add_u32_e32 v7, v19, v7

; #define LDS_WAIT() asm volatile("s_waitcnt lgkmcnt(0)" ::: "memory")
; __device__ __forceinline__ u32x2 s5_load_u(const bf16_t* U, int t0, int g, int lane) { if (t0 > T - 16) t0 = T - 16; return *(const u32x2*)(U + (size_t)(t0 + (lane >> 2)) * D + g * 16 + (lane & 3) * 4); }
; __device__ __forceinline__ void s5_item_setup(const S5Params& P, int g, int lane, LAS unsigned char* wlds, S5Item& L) {
;     ...
;         L.abr = mag * cosf(li * dt); L.abi = mag * sinf(li * dt);
;         const float n_re = L.abr - 1.0f, n_im = L.abi, den = lr * lr + li * li;
;         zt[lane * 2] = (n_re * lr + n_im * li) / den; zt[lane * 2 + 1] = (n_im * lr - n_re * li) / den;
;     }
;     LDS_WAIT(); __builtin_amdgcn_wave_barrier();
;     const int i0 = ((lane >> 4) & 1) * 8; const bool lo_half = lane >= 32;
; #pragma unroll
;     for (int f = 0; f < 8; ++f) {
;         const int pp = 16 * f + (lane & 15), p = pp >> 1; const bool im = pp & 1;
;         const float zr = zt[p * 2], zi = zt[p * 2 + 1];
;         const f32x4* br = (const f32x4*)(P.b_re + (size_t)(g * 64 + p) * 16 + i0); const f32x4* bi = (const f32x4*)(P.b_im + (size_t)(g * 64 + p) * 16 + i0);
;         float v[8];
; #pragma unroll
;         for (int q = 0; q < 2; ++q) { const f32x4 r = br[q], m = bi[q];
; #pragma unroll
;             for (int j = 0; j < 4; ++j) v[q * 4 + j] = im ? (zr * m[j] + zi * r[j]) : (zr * r[j] - zi * m[j]); }
;         u32x4 w;
; #pragma unroll
;         for (int q = 0; q < 4; ++q) { const unsigned h2 = cvt_pk_bf16(v[2 * q], v[2 * q + 1]);
;             const float r0 = v[2 * q] - bflo(h2), r1 = v[2 * q + 1] - bfhi(h2); w[q] = lo_half ? cvt_pk_bf16(r0, r1) : h2; }
;         L.bf[f] = __builtin_bit_cast(bf16x8, w);
; __device__ __forceinline__ void s5_scan1(LAS unsigned char* lds, const S5Params& P, const bf16_t* U, float* ES, int bid, int G) {
;     ...
;         u32x2 uq0 = s5_load_u(U, c * S5_L, g, lane), uq1 = s5_load_u(U, c * S5_L + 16, g, lane), uq2 = s5_load_u(U, c * S5_L + 32, g, lane), uq3 = s5_load_u(U, c * S5_L + 48, g, lane);
.LBB0_1178:
	s_or_b64 exec, exec, s[8:9]
	s_waitcnt vmcnt(0)
	v_mul_f32_e32 v6, v2, v6
	v_mul_f32_e32 v9, 0x3fb8aa3b, v6
	s_mov_b32 s1, 0x3fb8aa3b
	v_fma_f32 v10, v6, s1, -v9
	v_rndne_f32_e32 v13, v9
	v_fmac_f32_e32 v10, 0x32a5705f, v6
	v_sub_f32_e32 v9, v9, v13
	v_add_f32_e32 v9, v9, v10
	v_exp_f32_e32 v9, v9
	v_cvt_i32_f32_e32 v10, v13
	s_mov_b32 s1, 0xc2ce8ed0
	v_cmp_ngt_f32_e32 vcc, s1, v6
	s_mov_b32 s1, 0x42b17218
	v_ldexp_f32 v9, v9, v10
	v_cndmask_b32_e32 v9, 0, v9, vcc
	v_cmp_nlt_f32_e32 vcc, s1, v6
	s_brev_b32 s1, 1
	s_ashr_i32 s10, s101, 7
	v_cndmask_b32_e32 v6, v241, v9, vcc
	v_mul_f32_e32 v9, v8, v8
	v_fmamk_f32 v10, v9, 0xb94c1982, v182
	v_fmaak_f32 v10, v9, v10, 0xbe2aaa9d
	v_mul_f32_e32 v10, v9, v10
	v_fmac_f32_e32 v8, v8, v10
	v_fmamk_f32 v10, v9, 0x37d75334, v251
	v_fmaak_f32 v10, v9, v10, 0x3d2aabf7
	v_fmaak_f32 v10, v9, v10, 0xbf000004
	v_fma_f32 v9, v9, v10, 1.0
	v_and_b32_e32 v10, 1, v7
	v_cmp_eq_u32_e32 vcc, 0, v10
	v_lshlrev_b32_e32 v7, 30, v7
	v_mov_b32_e32 v10, 0x7fc00000
	v_cndmask_b32_e64 v8, -v8, v9, vcc
	v_bitop3_b32 v7, v7, v8, s1 bitop3:0x6c
	v_mul_f32_e32 v8, v12, v12
	v_fmamk_f32 v9, v8, 0xb94c1982, v182
	v_fmaak_f32 v9, v8, v9, 0xbe2aaa9d
	v_mul_f32_e32 v9, v8, v9
	v_fmac_f32_e32 v12, v12, v9
	v_fmamk_f32 v9, v8, 0x37d75334, v251
	v_fmaak_f32 v9, v8, v9, 0x3d2aabf7
	v_fmaak_f32 v9, v8, v9, 0xbf000004
	v_fma_f32 v8, v8, v9, 1.0
	v_and_b32_e32 v9, 1, v11
	s_movk_i32 s1, 0x1f8
	v_cmp_eq_u32_e64 s[8:9], 0, v9
	v_lshlrev_b32_e32 v9, 30, v11
	v_cmp_class_f32_e64 vcc, v4, s1
	v_and_b32_e32 v9, 0x80000000, v9
	v_xor_b32_e32 v4, v5, v4
	v_cndmask_b32_e64 v8, v8, v12, s[8:9]
	v_xor_b32_e32 v4, v4, v9
	v_xor_b32_e32 v4, v4, v8
	v_cndmask_b32_e32 v7, v10, v7, vcc
	v_cndmask_b32_e32 v4, v10, v4, vcc
	v_mul_f32_e32 v62, v6, v7
	v_mul_f32_e32 v65, v6, v4
	v_fma_f32 v64, v6, v7, -1.0
	v_mov_b32_e32 v6, v3
	v_pk_mul_f32 v[4:5], v[2:3], v[2:3]
	v_pk_mul_f32 v[6:7], v[6:7], v[64:65] op_sel:[0,1] op_sel_hi:[0,0]
	v_pk_fma_f32 v[8:9], v[2:3], v[64:65], v[6:7]
	v_pk_fma_f32 v[2:3], v[2:3], v[64:65], v[6:7] op_sel_hi:[0,1,1] neg_lo:[0,0,1] neg_hi:[0,0,1]
	v_pk_add_f32 v[4:5], v[4:5], v[4:5] op_sel:[0,1] op_sel_hi:[0,1]
	v_div_scale_f32 v2, s[8:9], v5, v5, v3
	v_rcp_f32_e32 v6, v2
	s_lshl_b32 s42, s0, 5
	v_add_u32_e32 v91, s45, v50
	v_mov_b32_e32 v61, v0
	v_fma_f32 v7, -v2, v6, 1.0
	v_fmac_f32_e32 v6, v7, v6
	v_div_scale_f32 v7, vcc, v3, v5, v3
	v_mul_f32_e32 v9, v7, v6
	v_fma_f32 v10, -v2, v9, v7
	v_fmac_f32_e32 v9, v10, v6
	v_fma_f32 v2, -v2, v9, v7
	v_div_fmas_f32 v2, v2, v6, v9
	v_div_fixup_f32 v3, v2, v5, v3
	v_div_scale_f32 v2, s[8:9], v4, v4, v8
	v_rcp_f32_e32 v5, v2
	s_lshl_b32 s8, s10, 8
	s_or_b32 s0, s8, 48
	s_min_i32 s0, s0, 0x1ff0
	v_fma_f32 v6, -v2, v5, 1.0
	v_fmac_f32_e32 v5, v6, v5
	v_div_scale_f32 v6, vcc, v8, v4, v8
	v_mul_f32_e32 v7, v6, v5
	v_fma_f32 v9, -v2, v7, v6
	v_fmac_f32_e32 v7, v9, v5
	v_fma_f32 v2, -v2, v7, v6
	v_div_fmas_f32 v2, v2, v5, v7
	v_div_fixup_f32 v2, v2, v4, v8
	ds_write_b64 v91, v[2:3] offset:13824
	v_or_b32_e32 v2, s0, v87
	v_ashrrev_i32_e32 v3, 31, v2
	v_lshlrev_b64 v[2:3], 12, v[2:3]
	v_lshl_add_u64 v[2:3], s[58:59], 0, v[2:3]
	v_lshl_add_u64 v[2:3], v[2:3], 0, s[42:43]
	s_or_b32 s0, s8, 32
	v_lshl_add_u64 v[2:3], v[2:3], 0, v[60:61]
	s_min_i32 s0, s0, 0x1ff0
	s_waitcnt lgkmcnt(0)
	global_load_dwordx2 v[70:71], v[2:3], off
	v_or_b32_e32 v2, s0, v87
	v_ashrrev_i32_e32 v3, 31, v2
	v_lshlrev_b64 v[2:3], 12, v[2:3]
	v_lshl_add_u64 v[2:3], s[58:59], 0, v[2:3]
	v_lshl_add_u64 v[2:3], v[2:3], 0, s[42:43]
	s_or_b32 s0, s8, 16
	v_lshl_add_u64 v[2:3], v[2:3], 0, v[60:61]
	s_min_i32 s0, s0, 0x1ff0
	global_load_dwordx2 v[68:69], v[2:3], off
	v_or_b32_e32 v2, s0, v87
	v_ashrrev_i32_e32 v3, 31, v2
	v_lshlrev_b64 v[2:3], 12, v[2:3]
	v_lshl_add_u64 v[2:3], s[58:59], 0, v[2:3]
	v_lshl_add_u64 v[2:3], v[2:3], 0, s[42:43]
	v_lshl_add_u64 v[2:3], v[2:3], 0, v[60:61]
	global_load_dwordx2 v[72:73], v[2:3], off
	v_or_b32_e32 v2, s8, v87
	v_ashrrev_i32_e32 v3, 31, v2
	v_lshlrev_b64 v[2:3], 12, v[2:3]
	v_lshl_add_u64 v[2:3], s[58:59], 0, v[2:3]
	v_lshl_add_u64 v[2:3], v[2:3], 0, s[42:43]
	v_lshl_add_u64 v[2:3], v[2:3], 0, v[60:61]
	global_load_dwordx2 v[76:77], v[2:3], off
	v_or_b32_e32 v2, s68, v86
	v_lshlrev_b32_e32 v2, 6, v2
	v_mov_b32_e32 v3, v0
	v_add_u32_e32 v30, 0x3000, v79
	v_lshl_add_u64 v[8:9], v[56:57], 0, v[2:3]
	v_lshl_add_u64 v[2:3], v[58:59], 0, v[2:3]
	ds_read2_b64 v[10:13], v30 offset0:240 offset1:248
	global_load_dwordx4 v[4:7], v[8:9], off offset:16
	global_load_dwordx4 v[14:17], v[8:9], off
	global_load_dwordx4 v[18:21], v[2:3], off offset:16
	global_load_dwordx4 v[22:25], v[2:3], off
	v_mov_b32_e32 v74, 0
	v_lshl_add_u64 v[66:67], v[52:53], 0, s[42:43]
	s_or_b32 s0, s8, 0xf0
	v_mov_b32_e32 v63, v62
	v_mov_b32_e32 v64, v65
	v_mov_b32_e32 v75, v74
	s_waitcnt vmcnt(0) lgkmcnt(0)
; __device__ __forceinline__ void s5_item_setup(const S5Params& P, int g, int lane, LAS unsigned char* wlds, S5Item& L) {
;     ...
;     for (int f = 0; f < 8; ++f) {
;         const int pp = 16 * f + (lane & 15), p = pp >> 1; const bool im = pp & 1;
;         const float zr = zt[p * 2], zi = zt[p * 2 + 1];
;         const f32x4* br = (const f32x4*)(P.b_re + (size_t)(g * 64 + p) * 16 + i0); const f32x4* bi = (const f32x4*)(P.b_im + (size_t)(g * 64 + p) * 16 + i0);
;         float v[8];
; #pragma unroll
;         for (int q = 0; q < 2; ++q) { const f32x4 r = br[q], m = bi[q];
; #pragma unroll
;             for (int j = 0; j < 4; ++j) v[q * 4 + j] = im ? (zr * m[j] + zi * r[j]) : (zr * r[j] - zi * m[j]); }
;         u32x4 w;
; #pragma unroll
;         for (int q = 0; q < 4; ++q) { const unsigned h2 = cvt_pk_bf16(v[2 * q], v[2 * q + 1]);
;             const float r0 = v[2 * q] - bflo(h2), r1 = v[2 * q + 1] - bfhi(h2); w[q] = lo_half ? cvt_pk_bf16(r0, r1) : h2; }
;         L.bf[f] = __builtin_bit_cast(bf16x8, w);
	v_pk_mul_f32 v[2:3], v[12:13], v[22:23] op_sel:[1,0]
	v_pk_mul_f32 v[8:9], v[12:13], v[22:23] op_sel_hi:[0,1]
	v_pk_fma_f32 v[2:3], v[12:13], v[14:15], v[2:3] op_sel_hi:[0,1,1] neg_lo:[0,0,1] neg_hi:[0,0,1]
	v_pk_fma_f32 v[8:9], v[12:13], v[14:15], v[8:9] op_sel:[1,0,0]
	s_nop 0
	v_cndmask_b32_e64 v3, v9, v3, s[6:7]
	v_cndmask_b32_e64 v2, v8, v2, s[6:7]
	v_cvt_pk_bf16_f32 v14, v2, v3
	v_lshlrev_b32_e32 v8, 16, v14
	v_and_b32_e32 v9, 0xffff0000, v14
	v_pk_add_f32 v[2:3], v[2:3], v[8:9] neg_lo:[0,1] neg_hi:[0,1]
	v_pk_mul_f32 v[8:9], v[12:13], v[24:25] op_sel:[1,0]
	v_cvt_pk_bf16_f32 v2, v2, v3
	v_cndmask_b32_e64 v2, v14, v2, s[4:5]
	v_pk_mul_f32 v[14:15], v[12:13], v[24:25] op_sel_hi:[0,1]
	v_pk_fma_f32 v[8:9], v[12:13], v[16:17], v[8:9] op_sel_hi:[0,1,1] neg_lo:[0,0,1] neg_hi:[0,0,1]
	v_pk_fma_f32 v[14:15], v[12:13], v[16:17], v[14:15] op_sel:[1,0,0]
	v_mov_b32_e32 v17, v0
	v_cndmask_b32_e64 v9, v15, v9, s[6:7]
	v_cndmask_b32_e64 v8, v14, v8, s[6:7]
	v_cvt_pk_bf16_f32 v3, v8, v9
	v_lshlrev_b32_e32 v14, 16, v3
	v_and_b32_e32 v15, 0xffff0000, v3
	v_pk_add_f32 v[8:9], v[8:9], v[14:15] neg_lo:[0,1] neg_hi:[0,1]
	v_pk_mul_f32 v[14:15], v[12:13], v[18:19] op_sel_hi:[0,1]
	v_cvt_pk_bf16_f32 v8, v8, v9
	v_cndmask_b32_e64 v3, v3, v8, s[4:5]
	v_pk_mul_f32 v[8:9], v[12:13], v[18:19] op_sel:[1,0]
	s_nop 0
	v_pk_fma_f32 v[8:9], v[12:13], v[4:5], v[8:9] op_sel_hi:[0,1,1] neg_lo:[0,0,1] neg_hi:[0,0,1]
	v_pk_fma_f32 v[4:5], v[12:13], v[4:5], v[14:15] op_sel:[1,0,0]
	s_nop 0
	v_cndmask_b32_e64 v5, v5, v9, s[6:7]
	v_cndmask_b32_e64 v4, v4, v8, s[6:7]
	v_cvt_pk_bf16_f32 v14, v4, v5
	v_lshlrev_b32_e32 v8, 16, v14
	v_and_b32_e32 v9, 0xffff0000, v14
	v_pk_add_f32 v[4:5], v[4:5], v[8:9] neg_lo:[0,1] neg_hi:[0,1]
	v_pk_mul_f32 v[8:9], v[12:13], v[20:21] op_sel:[1,0]
	v_cvt_pk_bf16_f32 v4, v4, v5
	v_cndmask_b32_e64 v4, v14, v4, s[4:5]
	v_pk_mul_f32 v[14:15], v[12:13], v[20:21] op_sel_hi:[0,1]
	v_pk_fma_f32 v[8:9], v[12:13], v[6:7], v[8:9] op_sel_hi:[0,1,1] neg_lo:[0,0,1] neg_hi:[0,0,1]
	v_pk_fma_f32 v[6:7], v[12:13], v[6:7], v[14:15] op_sel:[1,0,0]
	s_nop 0
	v_cndmask_b32_e64 v7, v7, v9, s[6:7]
	v_cndmask_b32_e64 v6, v6, v8, s[6:7]
	v_cvt_pk_bf16_f32 v5, v6, v7
	v_lshlrev_b32_e32 v8, 16, v5
	v_and_b32_e32 v9, 0xffff0000, v5
	v_pk_add_f32 v[6:7], v[6:7], v[8:9] neg_lo:[0,1] neg_hi:[0,1]
	s_nop 0
	v_cvt_pk_bf16_f32 v6, v6, v7
	v_cndmask_b32_e64 v5, v5, v6, s[4:5]
	v_or_b32_e32 v6, s68, v85
	v_lshlrev_b32_e32 v16, 6, v6
	v_lshl_add_u64 v[6:7], v[56:57], 0, v[16:17]
	v_lshl_add_u64 v[20:21], v[58:59], 0, v[16:17]
	global_load_dwordx4 v[12:15], v[6:7], off offset:16
	s_nop 0
	global_load_dwordx4 v[6:9], v[6:7], off
	s_nop 0
	global_load_dwordx4 v[16:19], v[20:21], off offset:16
	s_nop 0
	global_load_dwordx4 v[20:23], v[20:21], off
	s_waitcnt vmcnt(0)
	v_pk_mul_f32 v[24:25], v[10:11], v[20:21] op_sel:[1,0]
	v_pk_mul_f32 v[20:21], v[10:11], v[20:21] op_sel_hi:[0,1]
	v_pk_fma_f32 v[24:25], v[10:11], v[6:7], v[24:25] op_sel_hi:[0,1,1] neg_lo:[0,0,1] neg_hi:[0,0,1]
	v_pk_fma_f32 v[6:7], v[10:11], v[6:7], v[20:21] op_sel:[1,0,0]
	s_nop 0
	v_cndmask_b32_e64 v7, v7, v25, s[6:7]
	v_cndmask_b32_e64 v6, v6, v24, s[6:7]
	v_cvt_pk_bf16_f32 v24, v6, v7
	v_lshlrev_b32_e32 v20, 16, v24
	v_and_b32_e32 v21, 0xffff0000, v24
	v_pk_add_f32 v[6:7], v[6:7], v[20:21] neg_lo:[0,1] neg_hi:[0,1]
	v_pk_mul_f32 v[20:21], v[10:11], v[22:23] op_sel:[1,0]
	v_pk_mul_f32 v[22:23], v[10:11], v[22:23] op_sel_hi:[0,1]
	v_pk_fma_f32 v[20:21], v[10:11], v[8:9], v[20:21] op_sel_hi:[0,1,1] neg_lo:[0,0,1] neg_hi:[0,0,1]
	v_pk_fma_f32 v[8:9], v[10:11], v[8:9], v[22:23] op_sel:[1,0,0]
	v_cvt_pk_bf16_f32 v6, v6, v7
	v_cndmask_b32_e64 v9, v9, v21, s[6:7]
	v_cndmask_b32_e64 v8, v8, v20, s[6:7]
	v_cvt_pk_bf16_f32 v7, v8, v9
	v_lshlrev_b32_e32 v20, 16, v7
	v_and_b32_e32 v21, 0xffff0000, v7
	v_pk_add_f32 v[8:9], v[8:9], v[20:21] neg_lo:[0,1] neg_hi:[0,1]
	v_cndmask_b32_e64 v6, v24, v6, s[4:5]
	v_cvt_pk_bf16_f32 v8, v8, v9
	v_cndmask_b32_e64 v7, v7, v8, s[4:5]
	v_pk_mul_f32 v[8:9], v[10:11], v[16:17] op_sel:[1,0]
	v_pk_mul_f32 v[16:17], v[10:11], v[16:17] op_sel_hi:[0,1]
	v_pk_fma_f32 v[8:9], v[10:11], v[12:13], v[8:9] op_sel_hi:[0,1,1] neg_lo:[0,0,1] neg_hi:[0,0,1]
	v_pk_fma_f32 v[12:13], v[10:11], v[12:13], v[16:17] op_sel:[1,0,0]
	s_nop 0
	v_cndmask_b32_e64 v9, v13, v9, s[6:7]
	v_cndmask_b32_e64 v8, v12, v8, s[6:7]
	v_cvt_pk_bf16_f32 v16, v8, v9
	v_lshlrev_b32_e32 v12, 16, v16
	v_and_b32_e32 v13, 0xffff0000, v16
	v_pk_add_f32 v[8:9], v[8:9], v[12:13] neg_lo:[0,1] neg_hi:[0,1]
	v_pk_mul_f32 v[12:13], v[10:11], v[18:19] op_sel:[1,0]
	v_cvt_pk_bf16_f32 v8, v8, v9
	v_cndmask_b32_e64 v8, v16, v8, s[4:5]
	v_pk_mul_f32 v[16:17], v[10:11], v[18:19] op_sel_hi:[0,1]
	v_pk_fma_f32 v[12:13], v[10:11], v[14:15], v[12:13] op_sel_hi:[0,1,1] neg_lo:[0,0,1] neg_hi:[0,0,1]
	v_pk_fma_f32 v[10:11], v[10:11], v[14:15], v[16:17] op_sel:[1,0,0]
	ds_read2_b64 v[18:21], v30 offset0:224 offset1:232
	v_cndmask_b32_e64 v11, v11, v13, s[6:7]
	v_cndmask_b32_e64 v10, v10, v12, s[6:7]
	v_cvt_pk_bf16_f32 v9, v10, v11
	v_lshlrev_b32_e32 v12, 16, v9
	v_and_b32_e32 v13, 0xffff0000, v9
	v_pk_add_f32 v[10:11], v[10:11], v[12:13] neg_lo:[0,1] neg_hi:[0,1]
	s_nop 0
	v_cvt_pk_bf16_f32 v10, v10, v11
	v_cndmask_b32_e64 v9, v9, v10, s[4:5]
	v_or_b32_e32 v10, s68, v84
	v_lshlrev_b32_e32 v10, 6, v10
	v_mov_b32_e32 v11, v0
	v_lshl_add_u64 v[16:17], v[56:57], 0, v[10:11]
	v_lshl_add_u64 v[10:11], v[58:59], 0, v[10:11]
	global_load_dwordx4 v[12:15], v[16:17], off offset:16
	global_load_dwordx4 v[22:25], v[16:17], off
	global_load_dwordx4 v[26:29], v[10:11], off offset:16
	global_load_dwordx4 v[32:35], v[10:11], off
	s_waitcnt vmcnt(0) lgkmcnt(0)
; __device__ __forceinline__ void s5_item_setup(const S5Params& P, int g, int lane, LAS unsigned char* wlds, S5Item& L) {
;     ...
;     for (int f = 0; f < 8; ++f) {
;         const int pp = 16 * f + (lane & 15), p = pp >> 1; const bool im = pp & 1;
;         const float zr = zt[p * 2], zi = zt[p * 2 + 1];
;         const f32x4* br = (const f32x4*)(P.b_re + (size_t)(g * 64 + p) * 16 + i0); const f32x4* bi = (const f32x4*)(P.b_im + (size_t)(g * 64 + p) * 16 + i0);
;         float v[8];
; #pragma unroll
;         for (int q = 0; q < 2; ++q) { const f32x4 r = br[q], m = bi[q];
; #pragma unroll
;             for (int j = 0; j < 4; ++j) v[q * 4 + j] = im ? (zr * m[j] + zi * r[j]) : (zr * r[j] - zi * m[j]); }
;         u32x4 w;
; #pragma unroll
;         for (int q = 0; q < 4; ++q) { const unsigned h2 = cvt_pk_bf16(v[2 * q], v[2 * q + 1]);
;             const float r0 = v[2 * q] - bflo(h2), r1 = v[2 * q + 1] - bfhi(h2); w[q] = lo_half ? cvt_pk_bf16(r0, r1) : h2; }
;         L.bf[f] = __builtin_bit_cast(bf16x8, w);
	v_pk_mul_f32 v[10:11], v[20:21], v[32:33] op_sel:[1,0]
	v_pk_mul_f32 v[16:17], v[20:21], v[32:33] op_sel_hi:[0,1]
	v_pk_fma_f32 v[10:11], v[20:21], v[22:23], v[10:11] op_sel_hi:[0,1,1] neg_lo:[0,0,1] neg_hi:[0,0,1]
	v_pk_fma_f32 v[16:17], v[20:21], v[22:23], v[16:17] op_sel:[1,0,0]
	s_nop 0
	v_cndmask_b32_e64 v11, v17, v11, s[6:7]
	v_cndmask_b32_e64 v10, v16, v10, s[6:7]
	v_cvt_pk_bf16_f32 v22, v10, v11
	v_lshlrev_b32_e32 v16, 16, v22
	v_and_b32_e32 v17, 0xffff0000, v22
	v_pk_add_f32 v[10:11], v[10:11], v[16:17] neg_lo:[0,1] neg_hi:[0,1]
	v_pk_mul_f32 v[16:17], v[20:21], v[34:35] op_sel:[1,0]
	v_cvt_pk_bf16_f32 v10, v10, v11
	v_cndmask_b32_e64 v10, v22, v10, s[4:5]
	v_pk_mul_f32 v[22:23], v[20:21], v[34:35] op_sel_hi:[0,1]
	v_pk_fma_f32 v[16:17], v[20:21], v[24:25], v[16:17] op_sel_hi:[0,1,1] neg_lo:[0,0,1] neg_hi:[0,0,1]
	v_pk_fma_f32 v[22:23], v[20:21], v[24:25], v[22:23] op_sel:[1,0,0]
	v_mov_b32_e32 v25, v0
	v_cndmask_b32_e64 v17, v23, v17, s[6:7]
	v_cndmask_b32_e64 v16, v22, v16, s[6:7]
	v_cvt_pk_bf16_f32 v11, v16, v17
	v_lshlrev_b32_e32 v22, 16, v11
	v_and_b32_e32 v23, 0xffff0000, v11
	v_pk_add_f32 v[16:17], v[16:17], v[22:23] neg_lo:[0,1] neg_hi:[0,1]
	v_pk_mul_f32 v[22:23], v[20:21], v[26:27] op_sel_hi:[0,1]
	v_cvt_pk_bf16_f32 v16, v16, v17
	v_cndmask_b32_e64 v11, v11, v16, s[4:5]
	v_pk_mul_f32 v[16:17], v[20:21], v[26:27] op_sel:[1,0]
	s_nop 0
	v_pk_fma_f32 v[16:17], v[20:21], v[12:13], v[16:17] op_sel_hi:[0,1,1] neg_lo:[0,0,1] neg_hi:[0,0,1]
	v_pk_fma_f32 v[12:13], v[20:21], v[12:13], v[22:23] op_sel:[1,0,0]
	s_nop 0
	v_cndmask_b32_e64 v13, v13, v17, s[6:7]
	v_cndmask_b32_e64 v12, v12, v16, s[6:7]
	v_cvt_pk_bf16_f32 v22, v12, v13
	v_lshlrev_b32_e32 v16, 16, v22
	v_and_b32_e32 v17, 0xffff0000, v22
	v_pk_add_f32 v[12:13], v[12:13], v[16:17] neg_lo:[0,1] neg_hi:[0,1]
	v_pk_mul_f32 v[16:17], v[20:21], v[28:29] op_sel:[1,0]
	v_cvt_pk_bf16_f32 v12, v12, v13
	v_cndmask_b32_e64 v12, v22, v12, s[4:5]
	v_pk_mul_f32 v[22:23], v[20:21], v[28:29] op_sel_hi:[0,1]
	v_pk_fma_f32 v[16:17], v[20:21], v[14:15], v[16:17] op_sel_hi:[0,1,1] neg_lo:[0,0,1] neg_hi:[0,0,1]
	v_pk_fma_f32 v[14:15], v[20:21], v[14:15], v[22:23] op_sel:[1,0,0]
	s_nop 0
	v_cndmask_b32_e64 v15, v15, v17, s[6:7]
	v_cndmask_b32_e64 v14, v14, v16, s[6:7]
	v_cvt_pk_bf16_f32 v13, v14, v15
	v_lshlrev_b32_e32 v16, 16, v13
	v_and_b32_e32 v17, 0xffff0000, v13
	v_pk_add_f32 v[14:15], v[14:15], v[16:17] neg_lo:[0,1] neg_hi:[0,1]
	s_nop 0
	v_cvt_pk_bf16_f32 v14, v14, v15
	v_cndmask_b32_e64 v13, v13, v14, s[4:5]
	v_or_b32_e32 v14, s68, v83
	v_lshlrev_b32_e32 v24, 6, v14
	v_lshl_add_u64 v[14:15], v[56:57], 0, v[24:25]
	v_lshl_add_u64 v[28:29], v[58:59], 0, v[24:25]
	global_load_dwordx4 v[20:23], v[14:15], off offset:16
	s_nop 0
	global_load_dwordx4 v[14:17], v[14:15], off
	s_nop 0
	global_load_dwordx4 v[24:27], v[28:29], off offset:16
	global_load_dwordx4 v[32:35], v[28:29], off
	s_waitcnt vmcnt(0)
	v_pk_mul_f32 v[28:29], v[18:19], v[32:33] op_sel:[1,0]
	v_pk_mul_f32 v[32:33], v[18:19], v[32:33] op_sel_hi:[0,1]
	v_pk_fma_f32 v[28:29], v[18:19], v[14:15], v[28:29] op_sel_hi:[0,1,1] neg_lo:[0,0,1] neg_hi:[0,0,1]
	v_pk_fma_f32 v[14:15], v[18:19], v[14:15], v[32:33] op_sel:[1,0,0]
	v_pk_mul_f32 v[32:33], v[18:19], v[34:35] op_sel_hi:[0,1]
	v_cndmask_b32_e64 v15, v15, v29, s[6:7]
	v_cndmask_b32_e64 v14, v14, v28, s[6:7]
	v_cvt_pk_bf16_f32 v31, v14, v15
	v_lshlrev_b32_e32 v28, 16, v31
	v_and_b32_e32 v29, 0xffff0000, v31
	v_pk_add_f32 v[14:15], v[14:15], v[28:29] neg_lo:[0,1] neg_hi:[0,1]
	v_pk_mul_f32 v[28:29], v[18:19], v[34:35] op_sel:[1,0]
	v_cvt_pk_bf16_f32 v14, v14, v15
	v_pk_fma_f32 v[28:29], v[18:19], v[16:17], v[28:29] op_sel_hi:[0,1,1] neg_lo:[0,0,1] neg_hi:[0,0,1]
	v_pk_fma_f32 v[16:17], v[18:19], v[16:17], v[32:33] op_sel:[1,0,0]
	v_cndmask_b32_e64 v14, v31, v14, s[4:5]
	v_cndmask_b32_e64 v17, v17, v29, s[6:7]
	v_cndmask_b32_e64 v16, v16, v28, s[6:7]
	v_cvt_pk_bf16_f32 v15, v16, v17
	v_lshlrev_b32_e32 v28, 16, v15
	v_and_b32_e32 v29, 0xffff0000, v15
	v_pk_add_f32 v[16:17], v[16:17], v[28:29] neg_lo:[0,1] neg_hi:[0,1]
	s_nop 0
	v_cvt_pk_bf16_f32 v16, v16, v17
	v_cndmask_b32_e64 v15, v15, v16, s[4:5]
	v_pk_mul_f32 v[16:17], v[18:19], v[24:25] op_sel:[1,0]
	v_pk_mul_f32 v[24:25], v[18:19], v[24:25] op_sel_hi:[0,1]
	v_pk_fma_f32 v[16:17], v[18:19], v[20:21], v[16:17] op_sel_hi:[0,1,1] neg_lo:[0,0,1] neg_hi:[0,0,1]
	v_pk_fma_f32 v[20:21], v[18:19], v[20:21], v[24:25] op_sel:[1,0,0]
	s_nop 0
	v_cndmask_b32_e64 v17, v21, v17, s[6:7]
	v_cndmask_b32_e64 v16, v20, v16, s[6:7]
	v_cvt_pk_bf16_f32 v24, v16, v17
	v_lshlrev_b32_e32 v20, 16, v24
	v_and_b32_e32 v21, 0xffff0000, v24
	v_pk_add_f32 v[16:17], v[16:17], v[20:21] neg_lo:[0,1] neg_hi:[0,1]
	v_pk_mul_f32 v[20:21], v[18:19], v[26:27] op_sel:[1,0]
	v_cvt_pk_bf16_f32 v16, v16, v17
	v_cndmask_b32_e64 v16, v24, v16, s[4:5]
	v_pk_mul_f32 v[24:25], v[18:19], v[26:27] op_sel_hi:[0,1]
	v_pk_fma_f32 v[20:21], v[18:19], v[22:23], v[20:21] op_sel_hi:[0,1,1] neg_lo:[0,0,1] neg_hi:[0,0,1]
	v_pk_fma_f32 v[18:19], v[18:19], v[22:23], v[24:25] op_sel:[1,0,0]
	ds_read2_b64 v[26:29], v30 offset0:208 offset1:216
	v_cndmask_b32_e64 v19, v19, v21, s[6:7]
	v_cndmask_b32_e64 v18, v18, v20, s[6:7]
	v_cvt_pk_bf16_f32 v17, v18, v19
	v_lshlrev_b32_e32 v20, 16, v17
	v_and_b32_e32 v21, 0xffff0000, v17
	v_pk_add_f32 v[18:19], v[18:19], v[20:21] neg_lo:[0,1] neg_hi:[0,1]
	s_nop 0
	v_cvt_pk_bf16_f32 v18, v18, v19
	v_cndmask_b32_e64 v17, v17, v18, s[4:5]
	v_or_b32_e32 v18, s68, v82
	v_lshlrev_b32_e32 v18, 6, v18
	v_mov_b32_e32 v19, v0
	v_lshl_add_u64 v[24:25], v[56:57], 0, v[18:19]
	v_lshl_add_u64 v[18:19], v[58:59], 0, v[18:19]
	global_load_dwordx4 v[20:23], v[24:25], off offset:16
	global_load_dwordx4 v[32:35], v[24:25], off
	global_load_dwordx4 v[36:39], v[18:19], off offset:16
	global_load_dwordx4 v[40:43], v[18:19], off
	s_waitcnt vmcnt(0) lgkmcnt(0)
; __device__ __forceinline__ void s5_item_setup(const S5Params& P, int g, int lane, LAS unsigned char* wlds, S5Item& L) {
;     ...
;     for (int f = 0; f < 8; ++f) {
;         const int pp = 16 * f + (lane & 15), p = pp >> 1; const bool im = pp & 1;
;         const float zr = zt[p * 2], zi = zt[p * 2 + 1];
;         const f32x4* br = (const f32x4*)(P.b_re + (size_t)(g * 64 + p) * 16 + i0); const f32x4* bi = (const f32x4*)(P.b_im + (size_t)(g * 64 + p) * 16 + i0);
;         float v[8];
; #pragma unroll
;         for (int q = 0; q < 2; ++q) { const f32x4 r = br[q], m = bi[q];
; #pragma unroll
;             for (int j = 0; j < 4; ++j) v[q * 4 + j] = im ? (zr * m[j] + zi * r[j]) : (zr * r[j] - zi * m[j]); }
;         u32x4 w;
; #pragma unroll
;         for (int q = 0; q < 4; ++q) { const unsigned h2 = cvt_pk_bf16(v[2 * q], v[2 * q + 1]);
;             const float r0 = v[2 * q] - bflo(h2), r1 = v[2 * q + 1] - bfhi(h2); w[q] = lo_half ? cvt_pk_bf16(r0, r1) : h2; }
;         L.bf[f] = __builtin_bit_cast(bf16x8, w);
	v_pk_mul_f32 v[18:19], v[28:29], v[40:41] op_sel:[1,0]
	v_pk_mul_f32 v[24:25], v[28:29], v[40:41] op_sel_hi:[0,1]
	v_pk_fma_f32 v[18:19], v[28:29], v[32:33], v[18:19] op_sel_hi:[0,1,1] neg_lo:[0,0,1] neg_hi:[0,0,1]
	v_pk_fma_f32 v[24:25], v[28:29], v[32:33], v[24:25] op_sel:[1,0,0]
	v_pk_mul_f32 v[32:33], v[28:29], v[42:43] op_sel_hi:[0,1]
	v_cndmask_b32_e64 v19, v25, v19, s[6:7]
	v_cndmask_b32_e64 v18, v24, v18, s[6:7]
	v_cvt_pk_bf16_f32 v31, v18, v19
	v_lshlrev_b32_e32 v24, 16, v31
	v_and_b32_e32 v25, 0xffff0000, v31
	v_pk_add_f32 v[18:19], v[18:19], v[24:25] neg_lo:[0,1] neg_hi:[0,1]
	v_pk_mul_f32 v[24:25], v[28:29], v[42:43] op_sel:[1,0]
	v_pk_fma_f32 v[32:33], v[28:29], v[34:35], v[32:33] op_sel:[1,0,0]
	v_pk_fma_f32 v[24:25], v[28:29], v[34:35], v[24:25] op_sel_hi:[0,1,1] neg_lo:[0,0,1] neg_hi:[0,0,1]
	v_cndmask_b32_e64 v25, v33, v25, s[6:7]
	v_cndmask_b32_e64 v24, v32, v24, s[6:7]
	v_cvt_pk_bf16_f32 v18, v18, v19
	v_cvt_pk_bf16_f32 v19, v24, v25
	v_lshlrev_b32_e32 v32, 16, v19
	v_and_b32_e32 v33, 0xffff0000, v19
	v_pk_add_f32 v[24:25], v[24:25], v[32:33] neg_lo:[0,1] neg_hi:[0,1]
	v_pk_mul_f32 v[32:33], v[28:29], v[36:37] op_sel_hi:[0,1]
	v_cvt_pk_bf16_f32 v24, v24, v25
	v_cndmask_b32_e64 v19, v19, v24, s[4:5]
	v_pk_mul_f32 v[24:25], v[28:29], v[36:37] op_sel:[1,0]
	v_cndmask_b32_e64 v18, v31, v18, s[4:5]
	v_pk_fma_f32 v[24:25], v[28:29], v[20:21], v[24:25] op_sel_hi:[0,1,1] neg_lo:[0,0,1] neg_hi:[0,0,1]
	v_pk_fma_f32 v[20:21], v[28:29], v[20:21], v[32:33] op_sel:[1,0,0]
	v_pk_mul_f32 v[32:33], v[28:29], v[38:39] op_sel_hi:[0,1]
	v_cndmask_b32_e64 v21, v21, v25, s[6:7]
	v_cndmask_b32_e64 v20, v20, v24, s[6:7]
	v_cvt_pk_bf16_f32 v31, v20, v21
	v_lshlrev_b32_e32 v24, 16, v31
	v_and_b32_e32 v25, 0xffff0000, v31
	v_pk_add_f32 v[20:21], v[20:21], v[24:25] neg_lo:[0,1] neg_hi:[0,1]
	v_pk_mul_f32 v[24:25], v[28:29], v[38:39] op_sel:[1,0]
	v_cvt_pk_bf16_f32 v20, v20, v21
	v_pk_fma_f32 v[24:25], v[28:29], v[22:23], v[24:25] op_sel_hi:[0,1,1] neg_lo:[0,0,1] neg_hi:[0,0,1]
	v_pk_fma_f32 v[22:23], v[28:29], v[22:23], v[32:33] op_sel:[1,0,0]
	v_mov_b32_e32 v29, v0
	v_cndmask_b32_e64 v23, v23, v25, s[6:7]
	v_cndmask_b32_e64 v22, v22, v24, s[6:7]
	v_cvt_pk_bf16_f32 v21, v22, v23
	v_lshlrev_b32_e32 v24, 16, v21
	v_and_b32_e32 v25, 0xffff0000, v21
	v_pk_add_f32 v[22:23], v[22:23], v[24:25] neg_lo:[0,1] neg_hi:[0,1]
	v_cndmask_b32_e64 v20, v31, v20, s[4:5]
	v_cvt_pk_bf16_f32 v22, v22, v23
	v_cndmask_b32_e64 v21, v21, v22, s[4:5]
	v_or_b32_e32 v22, s68, v81
	v_lshlrev_b32_e32 v28, 6, v22
	v_lshl_add_u64 v[22:23], v[56:57], 0, v[28:29]
	v_lshl_add_u64 v[28:29], v[58:59], 0, v[28:29]
	global_load_dwordx4 v[32:35], v[22:23], off offset:16
	s_nop 0
	global_load_dwordx4 v[22:25], v[22:23], off
	s_nop 0
	global_load_dwordx4 v[36:39], v[28:29], off offset:16
	global_load_dwordx4 v[40:43], v[28:29], off
	s_waitcnt vmcnt(0)
	v_pk_mul_f32 v[28:29], v[26:27], v[40:41] op_sel:[1,0]
	v_pk_mul_f32 v[40:41], v[26:27], v[40:41] op_sel_hi:[0,1]
	v_pk_fma_f32 v[28:29], v[26:27], v[22:23], v[28:29] op_sel_hi:[0,1,1] neg_lo:[0,0,1] neg_hi:[0,0,1]
	v_pk_fma_f32 v[22:23], v[26:27], v[22:23], v[40:41] op_sel:[1,0,0]
	v_pk_mul_f32 v[40:41], v[26:27], v[42:43] op_sel_hi:[0,1]
	v_cndmask_b32_e64 v23, v23, v29, s[6:7]
	v_cndmask_b32_e64 v22, v22, v28, s[6:7]
	v_cvt_pk_bf16_f32 v31, v22, v23
	v_lshlrev_b32_e32 v28, 16, v31
	v_and_b32_e32 v29, 0xffff0000, v31
	v_pk_add_f32 v[22:23], v[22:23], v[28:29] neg_lo:[0,1] neg_hi:[0,1]
	v_pk_mul_f32 v[28:29], v[26:27], v[42:43] op_sel:[1,0]
	v_cvt_pk_bf16_f32 v22, v22, v23
	v_pk_fma_f32 v[28:29], v[26:27], v[24:25], v[28:29] op_sel_hi:[0,1,1] neg_lo:[0,0,1] neg_hi:[0,0,1]
	v_pk_fma_f32 v[24:25], v[26:27], v[24:25], v[40:41] op_sel:[1,0,0]
	v_cndmask_b32_e64 v22, v31, v22, s[4:5]
	v_cndmask_b32_e64 v25, v25, v29, s[6:7]
	v_cndmask_b32_e64 v24, v24, v28, s[6:7]
	v_cvt_pk_bf16_f32 v23, v24, v25
	v_lshlrev_b32_e32 v28, 16, v23
	v_and_b32_e32 v29, 0xffff0000, v23
	v_pk_add_f32 v[24:25], v[24:25], v[28:29] neg_lo:[0,1] neg_hi:[0,1]
	v_pk_mul_f32 v[28:29], v[26:27], v[36:37] op_sel_hi:[0,1]
	v_cvt_pk_bf16_f32 v24, v24, v25
	v_cndmask_b32_e64 v23, v23, v24, s[4:5]
	v_pk_mul_f32 v[24:25], v[26:27], v[36:37] op_sel:[1,0]
	v_pk_fma_f32 v[28:29], v[26:27], v[32:33], v[28:29] op_sel:[1,0,0]
	v_pk_fma_f32 v[24:25], v[26:27], v[32:33], v[24:25] op_sel_hi:[0,1,1] neg_lo:[0,0,1] neg_hi:[0,0,1]
	v_cndmask_b32_e64 v25, v29, v25, s[6:7]
	v_cndmask_b32_e64 v24, v28, v24, s[6:7]
	v_cvt_pk_bf16_f32 v31, v24, v25
	v_lshlrev_b32_e32 v28, 16, v31
	v_and_b32_e32 v29, 0xffff0000, v31
	v_pk_add_f32 v[24:25], v[24:25], v[28:29] neg_lo:[0,1] neg_hi:[0,1]
	v_pk_mul_f32 v[28:29], v[26:27], v[38:39] op_sel:[1,0]
	v_pk_mul_f32 v[32:33], v[26:27], v[38:39] op_sel_hi:[0,1]
	v_pk_fma_f32 v[28:29], v[26:27], v[34:35], v[28:29] op_sel_hi:[0,1,1] neg_lo:[0,0,1] neg_hi:[0,0,1]
	v_pk_fma_f32 v[26:27], v[26:27], v[34:35], v[32:33] op_sel:[1,0,0]
	v_cvt_pk_bf16_f32 v24, v24, v25
	v_cndmask_b32_e64 v27, v27, v29, s[6:7]
	v_cndmask_b32_e64 v26, v26, v28, s[6:7]
	v_cvt_pk_bf16_f32 v25, v26, v27
	v_lshlrev_b32_e32 v28, 16, v25
	v_and_b32_e32 v29, 0xffff0000, v25
	v_pk_add_f32 v[26:27], v[26:27], v[28:29] neg_lo:[0,1] neg_hi:[0,1]
	v_mov_b32_e32 v39, v0
	v_cvt_pk_bf16_f32 v26, v26, v27
	v_cndmask_b32_e64 v25, v25, v26, s[4:5]
	v_or_b32_e32 v26, s68, v80
	v_lshlrev_b32_e32 v38, 6, v26
	v_lshl_add_u64 v[26:27], v[56:57], 0, v[38:39]
	v_lshl_add_u64 v[42:43], v[58:59], 0, v[38:39]
	v_cndmask_b32_e64 v24, v31, v24, s[4:5]
	ds_read2_b64 v[30:33], v30 offset0:192 offset1:200
	global_load_dwordx4 v[34:37], v[26:27], off offset:16
	s_nop 0
	global_load_dwordx4 v[26:29], v[26:27], off
	s_nop 0
	global_load_dwordx4 v[38:41], v[42:43], off offset:16
	s_nop 0
	global_load_dwordx4 v[42:45], v[42:43], off
	s_waitcnt vmcnt(0) lgkmcnt(0)
; __device__ __forceinline__ void s5_item_setup(const S5Params& P, int g, int lane, LAS unsigned char* wlds, S5Item& L) {
;     ...
;     for (int f = 0; f < 8; ++f) {
;         const int pp = 16 * f + (lane & 15), p = pp >> 1; const bool im = pp & 1;
;         const float zr = zt[p * 2], zi = zt[p * 2 + 1];
;         const f32x4* br = (const f32x4*)(P.b_re + (size_t)(g * 64 + p) * 16 + i0); const f32x4* bi = (const f32x4*)(P.b_im + (size_t)(g * 64 + p) * 16 + i0);
;         float v[8];
; #pragma unroll
;         for (int q = 0; q < 2; ++q) { const f32x4 r = br[q], m = bi[q];
; #pragma unroll
;             for (int j = 0; j < 4; ++j) v[q * 4 + j] = im ? (zr * m[j] + zi * r[j]) : (zr * r[j] - zi * m[j]); }
;         u32x4 w;
; #pragma unroll
;         for (int q = 0; q < 4; ++q) { const unsigned h2 = cvt_pk_bf16(v[2 * q], v[2 * q + 1]);
;             const float r0 = v[2 * q] - bflo(h2), r1 = v[2 * q + 1] - bfhi(h2); w[q] = lo_half ? cvt_pk_bf16(r0, r1) : h2; }
;         L.bf[f] = __builtin_bit_cast(bf16x8, w);
	v_pk_mul_f32 v[46:47], v[32:33], v[42:43] op_sel:[1,0]
	v_pk_mul_f32 v[42:43], v[32:33], v[42:43] op_sel_hi:[0,1]
	v_pk_fma_f32 v[46:47], v[32:33], v[26:27], v[46:47] op_sel_hi:[0,1,1] neg_lo:[0,0,1] neg_hi:[0,0,1]
	v_pk_fma_f32 v[26:27], v[32:33], v[26:27], v[42:43] op_sel:[1,0,0]
	s_nop 0
	v_cndmask_b32_e64 v27, v27, v47, s[6:7]
	v_cndmask_b32_e64 v26, v26, v46, s[6:7]
	v_cvt_pk_bf16_f32 v46, v26, v27
	v_lshlrev_b32_e32 v42, 16, v46
	v_and_b32_e32 v43, 0xffff0000, v46
	v_pk_add_f32 v[26:27], v[26:27], v[42:43] neg_lo:[0,1] neg_hi:[0,1]
	v_pk_mul_f32 v[42:43], v[32:33], v[44:45] op_sel:[1,0]
	v_pk_mul_f32 v[44:45], v[32:33], v[44:45] op_sel_hi:[0,1]
	v_pk_fma_f32 v[42:43], v[32:33], v[28:29], v[42:43] op_sel_hi:[0,1,1] neg_lo:[0,0,1] neg_hi:[0,0,1]
	v_pk_fma_f32 v[28:29], v[32:33], v[28:29], v[44:45] op_sel:[1,0,0]
	v_cvt_pk_bf16_f32 v26, v26, v27
	v_cndmask_b32_e64 v29, v29, v43, s[6:7]
	v_cndmask_b32_e64 v28, v28, v42, s[6:7]
	v_cvt_pk_bf16_f32 v27, v28, v29
	v_lshlrev_b32_e32 v42, 16, v27
	v_and_b32_e32 v43, 0xffff0000, v27
	v_pk_add_f32 v[28:29], v[28:29], v[42:43] neg_lo:[0,1] neg_hi:[0,1]
	v_cndmask_b32_e64 v26, v46, v26, s[4:5]
	v_cvt_pk_bf16_f32 v28, v28, v29
	v_cndmask_b32_e64 v27, v27, v28, s[4:5]
	v_pk_mul_f32 v[28:29], v[32:33], v[38:39] op_sel:[1,0]
	v_pk_mul_f32 v[38:39], v[32:33], v[38:39] op_sel_hi:[0,1]
	v_pk_fma_f32 v[28:29], v[32:33], v[34:35], v[28:29] op_sel_hi:[0,1,1] neg_lo:[0,0,1] neg_hi:[0,0,1]
	v_pk_fma_f32 v[34:35], v[32:33], v[34:35], v[38:39] op_sel:[1,0,0]
	s_nop 0
	v_cndmask_b32_e64 v29, v35, v29, s[6:7]
	v_cndmask_b32_e64 v28, v34, v28, s[6:7]
	v_cvt_pk_bf16_f32 v38, v28, v29
	v_lshlrev_b32_e32 v34, 16, v38
	v_and_b32_e32 v35, 0xffff0000, v38
	v_pk_add_f32 v[28:29], v[28:29], v[34:35] neg_lo:[0,1] neg_hi:[0,1]
	v_pk_mul_f32 v[34:35], v[32:33], v[40:41] op_sel:[1,0]
	v_cvt_pk_bf16_f32 v28, v28, v29
	v_cndmask_b32_e64 v28, v38, v28, s[4:5]
	v_pk_mul_f32 v[38:39], v[32:33], v[40:41] op_sel_hi:[0,1]
	v_pk_fma_f32 v[34:35], v[32:33], v[36:37], v[34:35] op_sel_hi:[0,1,1] neg_lo:[0,0,1] neg_hi:[0,0,1]
	v_pk_fma_f32 v[32:33], v[32:33], v[36:37], v[38:39] op_sel:[1,0,0]
	s_nop 0
	v_cndmask_b32_e64 v33, v33, v35, s[6:7]
	v_cndmask_b32_e64 v32, v32, v34, s[6:7]
	v_cvt_pk_bf16_f32 v29, v32, v33
	v_lshlrev_b32_e32 v34, 16, v29
	v_and_b32_e32 v35, 0xffff0000, v29
	v_pk_add_f32 v[32:33], v[32:33], v[34:35] neg_lo:[0,1] neg_hi:[0,1]
	s_nop 0
	v_cvt_pk_bf16_f32 v32, v32, v33
	v_cndmask_b32_e64 v29, v29, v32, s[4:5]
	v_or_b32_e32 v32, s68, v78
	v_lshlrev_b32_e32 v32, 6, v32
	v_mov_b32_e32 v33, v0
	v_lshl_add_u64 v[38:39], v[56:57], 0, v[32:33]
	v_lshl_add_u64 v[32:33], v[58:59], 0, v[32:33]
	global_load_dwordx4 v[34:37], v[38:39], off offset:16
	global_load_dwordx4 v[42:45], v[38:39], off
	s_nop 0
	global_load_dwordx4 v[38:41], v[32:33], off offset:16
	global_load_dwordx4 v[46:49], v[32:33], off
	s_waitcnt vmcnt(0)
	v_pk_mul_f32 v[32:33], v[30:31], v[46:47] op_sel:[1,0]
	v_pk_mul_f32 v[46:47], v[30:31], v[46:47] op_sel_hi:[0,1]
	v_pk_fma_f32 v[32:33], v[30:31], v[42:43], v[32:33] op_sel_hi:[0,1,1] neg_lo:[0,0,1] neg_hi:[0,0,1]
	v_pk_fma_f32 v[42:43], v[30:31], v[42:43], v[46:47] op_sel:[1,0,0]
	s_nop 0
	v_cndmask_b32_e64 v33, v43, v33, s[6:7]
	v_cndmask_b32_e64 v32, v42, v32, s[6:7]
	v_cvt_pk_bf16_f32 v46, v32, v33
	v_lshlrev_b32_e32 v42, 16, v46
	v_and_b32_e32 v43, 0xffff0000, v46
	v_pk_add_f32 v[32:33], v[32:33], v[42:43] neg_lo:[0,1] neg_hi:[0,1]
	v_pk_mul_f32 v[42:43], v[30:31], v[48:49] op_sel:[1,0]
	v_cvt_pk_bf16_f32 v32, v32, v33
	v_cndmask_b32_e64 v32, v46, v32, s[4:5]
	v_pk_mul_f32 v[46:47], v[30:31], v[48:49] op_sel_hi:[0,1]
	v_pk_fma_f32 v[42:43], v[30:31], v[44:45], v[42:43] op_sel_hi:[0,1,1] neg_lo:[0,0,1] neg_hi:[0,0,1]
	v_pk_fma_f32 v[44:45], v[30:31], v[44:45], v[46:47] op_sel:[1,0,0]
	s_nop 0
	v_cndmask_b32_e64 v43, v45, v43, s[6:7]
	v_cndmask_b32_e64 v42, v44, v42, s[6:7]
	v_cvt_pk_bf16_f32 v33, v42, v43
	v_lshlrev_b32_e32 v44, 16, v33
	v_and_b32_e32 v45, 0xffff0000, v33
	v_pk_add_f32 v[42:43], v[42:43], v[44:45] neg_lo:[0,1] neg_hi:[0,1]
	s_nop 0
	v_cvt_pk_bf16_f32 v42, v42, v43
	v_cndmask_b32_e64 v33, v33, v42, s[4:5]
	v_pk_mul_f32 v[42:43], v[30:31], v[38:39] op_sel:[1,0]
	v_pk_mul_f32 v[38:39], v[30:31], v[38:39] op_sel_hi:[0,1]
	v_pk_fma_f32 v[42:43], v[30:31], v[34:35], v[42:43] op_sel_hi:[0,1,1] neg_lo:[0,0,1] neg_hi:[0,0,1]
	v_pk_fma_f32 v[34:35], v[30:31], v[34:35], v[38:39] op_sel:[1,0,0]
	s_nop 0
	v_cndmask_b32_e64 v35, v35, v43, s[6:7]
	v_cndmask_b32_e64 v34, v34, v42, s[6:7]
	v_cvt_pk_bf16_f32 v42, v34, v35
	v_lshlrev_b32_e32 v38, 16, v42
	v_and_b32_e32 v39, 0xffff0000, v42
	v_pk_add_f32 v[34:35], v[34:35], v[38:39] neg_lo:[0,1] neg_hi:[0,1]
	v_pk_mul_f32 v[38:39], v[30:31], v[40:41] op_sel:[1,0]
	v_pk_mul_f32 v[40:41], v[30:31], v[40:41] op_sel_hi:[0,1]
	v_pk_fma_f32 v[38:39], v[30:31], v[36:37], v[38:39] op_sel_hi:[0,1,1] neg_lo:[0,0,1] neg_hi:[0,0,1]
	v_pk_fma_f32 v[30:31], v[30:31], v[36:37], v[40:41] op_sel:[1,0,0]
	v_cvt_pk_bf16_f32 v34, v34, v35
	v_cndmask_b32_e64 v31, v31, v39, s[6:7]
	v_cndmask_b32_e64 v30, v30, v38, s[6:7]
	v_cvt_pk_bf16_f32 v35, v30, v31
	v_lshlrev_b32_e32 v36, 16, v35
	v_and_b32_e32 v37, 0xffff0000, v35
	v_pk_add_f32 v[30:31], v[30:31], v[36:37] neg_lo:[0,1] neg_hi:[0,1]
	v_cndmask_b32_e64 v34, v42, v34, s[4:5]
	v_cvt_pk_bf16_f32 v30, v30, v31
	v_cndmask_b32_e64 v35, v35, v30, s[4:5]
	v_mov_b32_e32 v30, v65
	v_mov_b32_e32 v31, v62
	v_mov_b32_e32 v36, v62
	v_mov_b32_e32 v37, v65

; #define LAS __attribute__((address_space(3)))
; __device__ __forceinline__ void s5_item_setup(const S5Params& P, int g, int lane, LAS unsigned char* wlds, S5Item& L) {
;     LAS float* zt = (LAS float*)(wlds + S5_OFF_Z);
;     {
;         const float lr = P.a_re[g * 64 + lane], li = P.a_im[g * 64 + lane], dt = expf(P.log_dt[g]);
;         const float mag = expf(lr * dt);
;         L.abr = mag * cosf(li * dt); L.abi = mag * sinf(li * dt);
; __device__ __forceinline__ void s5_scan2(LAS unsigned char* lds, const S5Params& P, const bf16_t* U, const float* ES, bf16_t* Gb, int bid, int G) {
;     ...
;     for (int item = gw; item < 128 * S5_NC; item += ngw) {
;         const int g = item & 127, c = item >> 7;
;         S5Item L; s5_item_setup(P, g, lane, wlds, L);
.LBB0_1235:
	s_mov_b32 s101, s34
	s_cmp_lg_u32 s82, 0x800
	s_cbranch_scc1 .Ls5perm_b
	s_bfe_u32 s101, s34, 0x30003
	s_lshl_b32 s101, s101, 9
	s_bfe_u32 s100, s34, 0x2000a
	s_lshl_b32 s100, s100, 7
	s_or_b32 s101, s101, s100
	s_bfe_u32 s100, s34, 0x40006
	s_lshl_b32 s100, s100, 3
	s_or_b32 s101, s101, s100
	s_and_b32 s100, s34, 7
	s_or_b32 s101, s101, s100
.Ls5perm_b:
	s_and_b32 s1, s101, 0x7f
	s_lshl_b32 s0, s1, 2
	v_mov_b32_e32 v1, s0
	global_load_dword v1, v1, s[20:21]
	s_lshl_b32 s22, s1, 6
	v_or_b32_e32 v2, s22, v176
	v_lshlrev_b32_e32 v2, 2, v2
	global_load_dword v3, v2, s[18:19]
	s_nop 0
	global_load_dword v2, v2, s[16:17]
	s_mov_b32 s0, 0x3fb8aa3b
	s_waitcnt vmcnt(2)
	v_mul_f32_e32 v4, 0x3fb8aa3b, v1
	v_fma_f32 v5, v1, s0, -v4
	v_rndne_f32_e32 v6, v4
	v_fmac_f32_e32 v5, 0x32a5705f, v1
	v_sub_f32_e32 v4, v4, v6
	v_add_f32_e32 v4, v4, v5
	v_cvt_i32_f32_e32 v6, v6
	v_exp_f32_e32 v4, v4
	s_mov_b32 s0, 0xc2ce8ed0
	v_cmp_ngt_f32_e32 vcc, s0, v1
	s_mov_b32 s0, 0x42b17218
	v_ldexp_f32 v4, v4, v6
	v_cndmask_b32_e32 v4, 0, v4, vcc
	v_cmp_nlt_f32_e32 vcc, s0, v1
	s_brev_b32 s0, 18
	s_nop 0
	v_cndmask_b32_e32 v5, v241, v4, vcc
	s_waitcnt vmcnt(1)
	v_mul_f32_e32 v1, v3, v5
	v_and_b32_e32 v4, 0x7fffffff, v1
	v_lshrrev_b32_e32 v6, 23, v4
	v_and_b32_e32 v7, 0x7fffff, v4
	v_cmp_nlt_f32_e64 s[14:15], |v1|, s0
	v_add_u32_e32 v9, 0xffffff88, v6
	v_or_b32_e32 v8, 0x800000, v7
	s_and_saveexec_b64 s[8:9], s[14:15]
	s_xor_b64 s[24:25], exec, s[8:9]
	s_cbranch_execz .LBB0_1237
	v_cmp_lt_u32_e32 vcc, 63, v9
	v_not_b32_e32 v6, 63
	v_not_b32_e32 v10, 31
	v_cndmask_b32_e32 v6, 0, v6, vcc
	v_add_u32_e32 v6, v6, v9
	v_cmp_lt_u32_e64 s[8:9], 31, v6
	s_mov_b32 s0, 0xfe5163ab
	v_mov_b32_e32 v11, v0
	v_cndmask_b32_e64 v7, 0, v10, s[8:9]
	v_add_u32_e32 v6, v7, v6
	v_cmp_lt_u32_e64 s[10:11], 31, v6
	v_mov_b32_e32 v13, v0
	v_mov_b32_e32 v15, v0
	v_cndmask_b32_e64 v7, 0, v10, s[10:11]
	v_add_u32_e32 v22, v7, v6
	v_mad_u64_u32 v[6:7], s[12:13], v8, s0, 0
	v_mov_b32_e32 v10, v7
	s_mov_b32 s0, 0x3c439041
	v_mad_u64_u32 v[10:11], s[12:13], v8, s0, v[10:11]
	v_mov_b32_e32 v12, v11
	s_mov_b32 s0, 0xdb629599
	v_mad_u64_u32 v[12:13], s[12:13], v8, s0, v[12:13]
	v_mov_b32_e32 v14, v13
	s_mov_b32 s0, 0xf534ddc0
	v_mad_u64_u32 v[14:15], s[12:13], v8, s0, v[14:15]
	v_mov_b32_e32 v16, v15
	v_mov_b32_e32 v17, v0
	s_mov_b32 s0, 0xfc2757d1
	v_mad_u64_u32 v[16:17], s[12:13], v8, s0, v[16:17]
	v_mov_b32_e32 v18, v17
	v_mov_b32_e32 v19, v0
	s_mov_b32 s0, 0x4e441529
	v_mad_u64_u32 v[18:19], s[12:13], v8, s0, v[18:19]
	v_mov_b32_e32 v20, v19
	v_mov_b32_e32 v21, v0
	s_mov_b32 s0, 0xa2f9836e
	v_mad_u64_u32 v[20:21], s[12:13], v8, s0, v[20:21]
	v_cndmask_b32_e32 v7, v18, v14, vcc
	v_cndmask_b32_e32 v11, v20, v16, vcc
	v_cndmask_b32_e32 v15, v21, v18, vcc
	v_cndmask_b32_e64 v13, v11, v7, s[8:9]
	v_cndmask_b32_e64 v11, v15, v11, s[8:9]
	v_cndmask_b32_e32 v15, v16, v12, vcc
	v_cndmask_b32_e64 v7, v7, v15, s[8:9]
	v_cndmask_b32_e32 v10, v14, v10, vcc
	v_cndmask_b32_e64 v11, v11, v13, s[10:11]
	v_cndmask_b32_e64 v13, v13, v7, s[10:11]
	v_sub_u32_e32 v16, 32, v22
	v_cndmask_b32_e64 v14, v15, v10, s[8:9]
	v_alignbit_b32 v17, v11, v13, v16
	v_cmp_eq_u32_e64 s[12:13], 0, v22
	v_cndmask_b32_e64 v7, v7, v14, s[10:11]
	v_alignbit_b32 v15, v13, v7, v16
	v_cndmask_b32_e64 v11, v17, v11, s[12:13]
	v_cndmask_b32_e32 v6, v12, v6, vcc
	v_cndmask_b32_e64 v13, v15, v13, s[12:13]
	v_bfe_u32 v18, v11, 29, 1
	v_cndmask_b32_e64 v6, v10, v6, s[8:9]
	v_alignbit_b32 v15, v11, v13, 30
	v_sub_u32_e32 v19, 0, v18
	v_cndmask_b32_e64 v6, v14, v6, s[10:11]
	v_xor_b32_e32 v15, v15, v19
	v_alignbit_b32 v10, v7, v6, v16
	v_cndmask_b32_e64 v7, v10, v7, s[12:13]
	v_ffbh_u32_e32 v12, v15
	v_alignbit_b32 v10, v13, v7, 30
	v_min_u32_e32 v12, 32, v12
	v_alignbit_b32 v6, v7, v6, 30
	v_xor_b32_e32 v10, v10, v19
	v_sub_u32_e32 v13, 31, v12
	v_xor_b32_e32 v6, v6, v19
	v_alignbit_b32 v14, v15, v10, v13
	v_alignbit_b32 v6, v10, v6, v13
	v_alignbit_b32 v7, v14, v6, 9
	v_ffbh_u32_e32 v10, v7
	v_min_u32_e32 v10, 32, v10
	v_lshrrev_b32_e32 v17, 29, v11
	v_not_b32_e32 v13, v10
	v_alignbit_b32 v6, v7, v6, v13
	v_lshlrev_b32_e32 v7, 31, v17
	v_or_b32_e32 v13, 0x33000000, v7
	v_add_lshl_u32 v10, v10, v12, 23
	v_lshrrev_b32_e32 v6, 9, v6
	v_sub_u32_e32 v10, v13, v10
	v_or_b32_e32 v7, 0.5, v7
	v_lshlrev_b32_e32 v12, 23, v12
	v_or_b32_e32 v6, v10, v6
	v_lshrrev_b32_e32 v10, 9, v14
	v_sub_u32_e32 v7, v7, v12
	v_or_b32_e32 v7, v10, v7
	v_mul_f32_e32 v10, 0x3fc90fda, v7
	s_mov_b32 s0, 0x3fc90fda
	v_fma_f32 v12, v7, s0, -v10
	v_fmac_f32_e32 v12, 0x33a22168, v7
	v_fmac_f32_e32 v12, 0x3fc90fda, v6
	v_lshrrev_b32_e32 v6, 30, v11
	v_add_f32_e32 v7, v10, v12
	v_add_u32_e32 v6, v18, v6

; #define LDS_WAIT() asm volatile("s_waitcnt lgkmcnt(0)" ::: "memory")
; __device__ __forceinline__ void s5_item_setup(const S5Params& P, int g, int lane, LAS unsigned char* wlds, S5Item& L) {
;     ...
;         L.abr = mag * cosf(li * dt); L.abi = mag * sinf(li * dt);
;         const float n_re = L.abr - 1.0f, n_im = L.abi, den = lr * lr + li * li;
;         zt[lane * 2] = (n_re * lr + n_im * li) / den; zt[lane * 2 + 1] = (n_im * lr - n_re * li) / den;
;     }
;     LDS_WAIT(); __builtin_amdgcn_wave_barrier();
;     const int i0 = ((lane >> 4) & 1) * 8; const bool lo_half = lane >= 32;
; #pragma unroll
;     for (int f = 0; f < 8; ++f) {
;         const int pp = 16 * f + (lane & 15), p = pp >> 1; const bool im = pp & 1;
;         const float zr = zt[p * 2], zi = zt[p * 2 + 1];
;         const f32x4* br = (const f32x4*)(P.b_re + (size_t)(g * 64 + p) * 16 + i0); const f32x4* bi = (const f32x4*)(P.b_im + (size_t)(g * 64 + p) * 16 + i0);
.LBB0_1243:
	s_or_b64 exec, exec, s[8:9]
	s_waitcnt vmcnt(0)
	v_mul_f32_e32 v5, v2, v5
	v_mul_f32_e32 v8, 0x3fb8aa3b, v5
	s_mov_b32 s0, 0x3fb8aa3b
	v_fma_f32 v9, v5, s0, -v8
	v_rndne_f32_e32 v12, v8
	v_fmac_f32_e32 v9, 0x32a5705f, v5
	v_sub_f32_e32 v8, v8, v12
	v_add_f32_e32 v8, v8, v9
	v_cvt_i32_f32_e32 v9, v12
	v_exp_f32_e32 v8, v8
	s_mov_b32 s0, 0xc2ce8ed0
	v_cmp_ngt_f32_e32 vcc, s0, v5
	s_mov_b32 s0, 0x42b17218
	v_ldexp_f32 v8, v8, v9
	v_cndmask_b32_e32 v8, 0, v8, vcc
	v_cmp_nlt_f32_e32 vcc, s0, v5
	v_mul_f32_e32 v5, v7, v7
	s_brev_b32 s0, 1
	v_cndmask_b32_e32 v44, v241, v8, vcc
	v_fmamk_f32 v8, v5, 0xb94c1982, v182
	v_fmaak_f32 v8, v5, v8, 0xbe2aaa9d
	v_mul_f32_e32 v8, v5, v8
	v_fmac_f32_e32 v7, v7, v8
	v_fmamk_f32 v8, v5, 0x37d75334, v251
	v_fmaak_f32 v8, v5, v8, 0x3d2aabf7
	v_fmaak_f32 v8, v5, v8, 0xbf000004
	v_fma_f32 v5, v5, v8, 1.0
	v_and_b32_e32 v8, 1, v6
	v_cmp_eq_u32_e32 vcc, 0, v8
	v_lshlrev_b32_e32 v6, 30, v6
	v_mov_b32_e32 v8, v3
	v_cndmask_b32_e64 v5, -v7, v5, vcc
	v_bitop3_b32 v5, v6, v5, s0 bitop3:0x6c
	s_movk_i32 s0, 0x1f8
	v_cmp_class_f32_e64 vcc, v1, s0
	v_mov_b32_e32 v7, 0x7fc00000
	v_xor_b32_e32 v1, v4, v1
	v_cndmask_b32_e32 v45, v7, v5, vcc
	v_mul_f32_e32 v5, v11, v11
	v_fmamk_f32 v6, v5, 0xb94c1982, v182
	v_fmaak_f32 v6, v5, v6, 0xbe2aaa9d
	v_mul_f32_e32 v6, v5, v6
	v_fmac_f32_e32 v11, v11, v6
	v_fmamk_f32 v6, v5, 0x37d75334, v251
	v_fmaak_f32 v6, v5, v6, 0x3d2aabf7
	v_fmaak_f32 v6, v5, v6, 0xbf000004
	v_fma_f32 v5, v5, v6, 1.0
	v_and_b32_e32 v6, 1, v10
	v_cmp_eq_u32_e64 s[8:9], 0, v6
	v_lshlrev_b32_e32 v6, 30, v10
	v_and_b32_e32 v6, 0x80000000, v6
	v_cndmask_b32_e64 v5, v5, v11, s[8:9]
	v_xor_b32_e32 v1, v1, v6
	v_xor_b32_e32 v1, v1, v5
	v_cndmask_b32_e32 v1, v7, v1, vcc
	v_mul_f32_e32 v164, v44, v1
	v_fma_f32 v4, v44, v45, -1.0
	v_mov_b32_e32 v5, v164
	v_pk_mul_f32 v[6:7], v[2:3], v[2:3]
	v_pk_mul_f32 v[8:9], v[8:9], v[4:5] op_sel:[0,1] op_sel_hi:[0,0]
	v_pk_fma_f32 v[10:11], v[2:3], v[4:5], v[8:9] op_sel_hi:[0,1,1] neg_lo:[0,0,1] neg_hi:[0,0,1]
	v_pk_add_f32 v[6:7], v[6:7], v[6:7] op_sel:[0,1] op_sel_hi:[0,1]
	v_div_scale_f32 v1, s[8:9], v7, v7, v11
	v_rcp_f32_e32 v10, v1
	v_pk_fma_f32 v[2:3], v[2:3], v[4:5], v[8:9]
	v_mul_f32_e32 v166, v44, v45
	v_add_f32_e32 v163, v166, v166
	v_fma_f32 v3, -v1, v10, 1.0
	v_fmac_f32_e32 v10, v3, v10
	v_div_scale_f32 v3, vcc, v11, v7, v11
	v_mul_f32_e32 v4, v3, v10
	v_fma_f32 v5, -v1, v4, v3
	v_fmac_f32_e32 v4, v5, v10
	v_div_scale_f32 v5, s[8:9], v6, v6, v2
	v_rcp_f32_e32 v8, v5
	v_fma_f32 v1, -v1, v4, v3
	v_div_fmas_f32 v1, v1, v10, v4
	v_div_fixup_f32 v3, v1, v7, v11
	v_fma_f32 v1, -v5, v8, 1.0
	v_fmac_f32_e32 v8, v1, v8
	v_div_scale_f32 v1, vcc, v2, v6, v2
	v_mul_f32_e32 v4, v1, v8
	v_fma_f32 v7, -v5, v4, v1
	v_fmac_f32_e32 v4, v7, v8
	v_fma_f32 v1, -v5, v4, v1
	v_div_fmas_f32 v1, v1, v8, v4
	v_div_fixup_f32 v2, v1, v6, v2
	v_or_b32_e32 v1, s22, v178
	ds_write_b64 v200, v[2:3] offset:13824
	v_lshlrev_b32_e32 v2, 6, v1
	v_mov_b32_e32 v3, v0
	v_lshl_add_u64 v[4:5], v[152:153], 0, v[2:3]
	v_lshl_add_u64 v[6:7], v[154:155], 0, v[2:3]
	v_or_b32_e32 v1, s22, v181
	s_waitcnt lgkmcnt(0)
; __device__ __forceinline__ void s5_item_setup(const S5Params& P, int g, int lane, LAS unsigned char* wlds, S5Item& L) {
;     ...
;     for (int f = 0; f < 8; ++f) {
;         const int pp = 16 * f + (lane & 15), p = pp >> 1; const bool im = pp & 1;
;         const float zr = zt[p * 2], zi = zt[p * 2 + 1];
;         const f32x4* br = (const f32x4*)(P.b_re + (size_t)(g * 64 + p) * 16 + i0); const f32x4* bi = (const f32x4*)(P.b_im + (size_t)(g * 64 + p) * 16 + i0);
;         float v[8];
; #pragma unroll
;         for (int q = 0; q < 2; ++q) { const f32x4 r = br[q], m = bi[q];
; __device__ __forceinline__ void s5_scan2(LAS unsigned char* lds, const S5Params& P, const bf16_t* U, const float* ES, bf16_t* Gb, int bid, int G) {
;     ...
;         float pr = L.abr, pi = L.abi;
; #pragma unroll
;         for (int i = 0; i < 8; ++i) { const float nr = pr * pr - pi * pi, ni = 2.0f * pr * pi; pr = nr; pi = ni; }
;         float sre = 0.f, sim = 0.f;
;         {
;             const float* ep = ES + ((size_t)(g * S5_NC) * 64 + lane) * 2; int cc = 0;
;             for (; cc + 8 <= c; cc += 8) { f32x2 e[8];
	global_load_dwordx4 v[132:135], v[4:5], off offset:16
	s_nop 0
	global_load_dwordx4 v[2:5], v[4:5], off
	s_nop 0
	global_load_dwordx4 v[136:139], v[6:7], off offset:16
	global_load_dwordx4 v[144:147], v[6:7], off
	v_lshlrev_b32_e32 v6, 6, v1
	v_mov_b32_e32 v7, v0
	v_lshl_add_u64 v[8:9], v[152:153], 0, v[6:7]
	v_lshl_add_u64 v[10:11], v[154:155], 0, v[6:7]
	v_or_b32_e32 v1, s22, v183
	global_load_dwordx4 v[120:123], v[8:9], off offset:16
	s_nop 0
	global_load_dwordx4 v[6:9], v[8:9], off
	s_nop 0
	global_load_dwordx4 v[124:127], v[10:11], off offset:16
	global_load_dwordx4 v[128:131], v[10:11], off
	v_lshlrev_b32_e32 v10, 6, v1
	v_mov_b32_e32 v11, v0
	v_lshl_add_u64 v[12:13], v[152:153], 0, v[10:11]
	v_lshl_add_u64 v[14:15], v[154:155], 0, v[10:11]
	v_or_b32_e32 v1, s22, v184
	global_load_dwordx4 v[108:111], v[12:13], off offset:16
	s_nop 0
	global_load_dwordx4 v[10:13], v[12:13], off
	s_nop 0
	global_load_dwordx4 v[112:115], v[14:15], off offset:16
	global_load_dwordx4 v[116:119], v[14:15], off
	v_lshlrev_b32_e32 v14, 6, v1
	v_mov_b32_e32 v15, v0
	v_lshl_add_u64 v[16:17], v[152:153], 0, v[14:15]
	v_lshl_add_u64 v[18:19], v[154:155], 0, v[14:15]
	v_or_b32_e32 v1, s22, v185
	global_load_dwordx4 v[92:95], v[16:17], off offset:16
	s_nop 0
	global_load_dwordx4 v[14:17], v[16:17], off
	s_nop 0
	global_load_dwordx4 v[96:99], v[18:19], off offset:16
	global_load_dwordx4 v[100:103], v[18:19], off
	v_lshlrev_b32_e32 v18, 6, v1
	v_mov_b32_e32 v19, v0
	v_lshl_add_u64 v[20:21], v[152:153], 0, v[18:19]
	v_lshl_add_u64 v[22:23], v[154:155], 0, v[18:19]
	v_or_b32_e32 v1, s22, v187
	global_load_dwordx4 v[80:83], v[20:21], off offset:16
	s_nop 0
	global_load_dwordx4 v[18:21], v[20:21], off
	s_nop 0
	global_load_dwordx4 v[84:87], v[22:23], off offset:16
	global_load_dwordx4 v[88:91], v[22:23], off
	v_lshlrev_b32_e32 v22, 6, v1
	v_mov_b32_e32 v23, v0
	v_lshl_add_u64 v[24:25], v[152:153], 0, v[22:23]
	v_lshl_add_u64 v[26:27], v[154:155], 0, v[22:23]
	v_or_b32_e32 v1, s22, v188
	global_load_dwordx4 v[64:67], v[24:25], off offset:16
	s_nop 0
	global_load_dwordx4 v[22:25], v[24:25], off
	s_nop 0
	global_load_dwordx4 v[68:71], v[26:27], off offset:16
	global_load_dwordx4 v[76:79], v[26:27], off
	v_lshlrev_b32_e32 v26, 6, v1
	v_mov_b32_e32 v27, v0
	v_lshl_add_u64 v[28:29], v[152:153], 0, v[26:27]
	v_lshl_add_u64 v[30:31], v[154:155], 0, v[26:27]
	v_or_b32_e32 v1, s22, v189
	global_load_dwordx4 v[32:35], v[28:29], off offset:16
	s_nop 0
	global_load_dwordx4 v[26:29], v[28:29], off
	s_nop 0
	global_load_dwordx4 v[56:59], v[30:31], off offset:16
	global_load_dwordx4 v[60:63], v[30:31], off
	v_lshlrev_b32_e32 v30, 6, v1
	v_mov_b32_e32 v31, v0
	v_lshl_add_u64 v[40:41], v[152:153], 0, v[30:31]
	v_lshl_add_u64 v[30:31], v[154:155], 0, v[30:31]
	global_load_dwordx4 v[36:39], v[40:41], off offset:16
	global_load_dwordx4 v[48:51], v[40:41], off
	s_nop 0
	global_load_dwordx4 v[40:43], v[30:31], off offset:16
	global_load_dwordx4 v[52:55], v[30:31], off
	v_add_u32_e32 v1, 0x3000, v179
	ds_read2_b64 v[140:143], v1 offset0:192 offset1:200
	ds_read2_b64 v[104:107], v1 offset0:208 offset1:216
	ds_read2_b64 v[72:75], v1 offset0:224 offset1:232
	ds_read2_b64 v[44:47], v1 offset0:240 offset1:248
	v_mul_f32_e32 v1, v164, v164
	v_mul_f32_e32 v163, v163, v164
	v_fma_f32 v1, v166, v166, -v1
	v_mul_f32_e32 v165, v163, v163
	v_fma_f32 v165, v1, v1, -v165
	v_add_f32_e32 v1, v1, v1
	v_mul_f32_e32 v1, v163, v1
	v_mul_f32_e32 v163, v1, v1
	v_fma_f32 v163, v165, v165, -v163
	v_add_f32_e32 v165, v165, v165
	v_mul_f32_e32 v1, v1, v165
	v_mul_f32_e32 v165, v1, v1
	v_fma_f32 v165, v163, v163, -v165
	v_add_f32_e32 v163, v163, v163
	v_mul_f32_e32 v1, v1, v163
	v_mul_f32_e32 v163, v1, v1
	v_fma_f32 v163, v165, v165, -v163
	v_add_f32_e32 v165, v165, v165
	v_mul_f32_e32 v1, v1, v165
	v_mul_f32_e32 v165, v1, v1
	v_fma_f32 v165, v163, v163, -v165
	v_add_f32_e32 v163, v163, v163
	v_mul_f32_e32 v1, v1, v163
	v_mul_f32_e32 v163, v1, v1
	v_fma_f32 v163, v165, v165, -v163
	v_add_f32_e32 v165, v165, v165
	v_mul_f32_e32 v1, v1, v165
	s_and_b32 s0, s101, 0x7f
	v_mul_f32_e32 v165, v1, v1
	v_lshl_or_b32 v30, s0, 14, v195
	s_ashr_i32 s0, s101, 7
	v_fma_f32 v170, v163, v163, -v165
	v_add_f32_e32 v163, v163, v163
	s_mov_b32 s42, 0
	v_mov_b32_e32 v31, v0
	s_cmp_lt_i32 s0, 8
	v_mul_f32_e32 v172, v1, v163
	s_cbranch_scc1 .LBB0_1247
	v_mov_b32_e32 v168, 0
	v_lshl_add_u64 v[174:175], s[28:29], 0, v[30:31]
	v_mov_b32_e32 v171, v170
	v_mov_b32_e32 v173, v172
	v_mov_b32_e32 v169, v168
